# attention: static s_setprio 1 for the four waves that do the half-merge (hf==0) for the whole attention phase, reset at phase end
# baseline (speedup 1.0000x reference)
; #define LAS __attribute__((address_space(3)))
; __device__ __forceinline__ void attn_phase(const bf16_t* Q, const bf16_t* Kb, const bf16_t* VTa, const float* rpb, bf16_t* Y, LAS unsigned char* lds, int bx, int G, int tid, int wave, int lane) {
;     const int g = wave & 3, hf = wave >> 2;
;     const int fr = lane & 15, fq = lane >> 4;
;     const int cs = (g == 0) ? 0 : ((g == 1) ? 8 : ((g == 2) ? 24 : 32));
;     const int c = 16 * g + fr;
;     const int colstart = min(max(c - 8, 0), 48);
;     const int kc0 = cs + 8 * fq;
;     const int dci0 = kc0 - c + 15;
;     const int wlo = max(colstart - kc0, 0), wwd = max(min(colstart + 16 - kc0, 8) - wlo, 0);
;     LAS unsigned char* KL = lds; LAS unsigned char* VL = lds + 65536; LAS float* rl = (LAS float*)(lds + 131072);
;     const int lr = lane >> 3, lc = lane & 7;
.LBB0_445:
	v_readlane_b32 s12, v254, 57
	v_readlane_b32 s13, v254, 58
	s_add_u32 s18, s0, 0x1fc00000
	v_lshrrev_b32_e32 v39, 4, v220
	v_cndmask_b32_e64 v0, 0, 1, s[12:13]
	v_cmp_ne_u32_e64 s[16:17], 1, v0
	s_addc_u32 s19, s1, 0
	v_and_b32_e32 v219, 15, v218
	v_writelane_b32 v163, s16, 43
	s_andn2_b64 vcc, exec, s[12:13]
	v_and_b32_e32 v43, 7, v218
	v_lshlrev_b32_e32 v40, 4, v39
	v_lshlrev_b32_e32 v38, 2, v39
	v_writelane_b32 v163, s17, 44
	s_cbranch_vccnz .LBB0_470
	v_lshl_or_b32 v47, s20, 4, v219
	v_sub_u32_e64 v0, v47, 8 clamp
	v_min_u32_e32 v2, 48, v0
	v_lshlrev_b32_e32 v0, 3, v39
	v_add_u32_e32 v3, s22, v0
	v_sub_u32_e32 v2, v2, v3
	v_add_u32_e32 v4, 16, v2
	v_min_i32_e32 v4, 8, v4
	v_max_i32_e32 v5, 0, v2
	s_add_u32 s62, s0, 0x17c00000
	v_sub_u32_e32 v2, v4, v5
	s_addc_u32 s63, s1, 0
	v_max_i32_e32 v7, 0, v2
	v_sub_u32_e32 v2, v3, v47
	v_writelane_b32 v163, s46, 47
	s_add_u32 s21, s0, 0x18c00000
	v_add_u32_e32 v46, 0xe8, v2
	v_lshlrev_b32_e32 v2, 1, v220
	v_writelane_b32 v163, s47, 48
	s_addc_u32 s83, s1, 0
	v_and_b32_e32 v3, 24, v2
	s_add_u32 s34, s0, 0x1ac00000
	v_readlane_b32 s12, v163, 39
	v_add_u32_e32 v3, s22, v3
	s_addc_u32 s35, s1, 0
	s_mulk_i32 s12, 0x7440
	v_and_or_b32 v11, v218, 3, v3
	v_bfe_u32 v3, v3, 3, 2
	v_and_b32_e32 v2, 4, v2
	s_add_u32 s16, s78, s12
	s_movk_i32 s12, 0x1d1
	v_mov_b32_e32 v41, v1
	v_bitop3_b32 v6, v3, v39, v2 bitop3:0x36
	s_addc_u32 s17, s79, 0
	v_lshrrev_b32_e32 v4, 2, v220
	v_cmp_gt_i32_e64 s[38:39], s12, v218
	v_lshl_add_u64 v[44:45], s[62:63], 0, v[40:41]
	v_lshlrev_b32_e32 v41, 4, v6
	v_or_b32_e32 v6, 4, v39
	s_lshr_b32 s12, s22, 3
	v_lshrrev_b32_e32 v42, 3, v220
	v_and_b32_e32 v9, 4, v4
	v_bitop3_b32 v2, v3, v6, v2 bitop3:0x36
	v_add_u32_e32 v6, s12, v39
	v_lshrrev_b32_e32 v8, 1, v218
	v_lshlrev_b32_e32 v55, 4, v2
	v_bitop3_b32 v2, v9, v43, s20 bitop3:0x36
	v_bitop3_b32 v6, v6, v8, 7 bitop3:0x78
	v_bitop3_b32 v8, v9, v43, 1 bitop3:0x36
	v_bitop3_b32 v12, v9, v43, 2 bitop3:0x36
	v_or_b32_e32 v56, 24, v42
	v_bitop3_b32 v9, v9, v43, 3 bitop3:0x36
	v_lshlrev_b32_e32 v14, 3, v9
	v_lshrrev_b32_e32 v9, 1, v56
	v_xor_b32_e32 v9, v9, v220
	v_lshlrev_b32_e32 v9, 3, v9
	v_or_b32_e32 v60, 40, v42
	v_and_b32_e32 v16, 56, v9
	v_lshrrev_b32_e32 v9, 1, v60
	v_xor_b32_e32 v9, v9, v220
	v_lshlrev_b32_e32 v9, 3, v9
	v_or_b32_e32 v64, 56, v42
	v_and_b32_e32 v18, 56, v9
	v_lshrrev_b32_e32 v9, 1, v64
	v_xor_b32_e32 v9, v9, v220
	v_lshlrev_b32_e32 v9, 3, v9
	v_lshl_or_b32 v48, s82, 3, v42
	v_and_b32_e32 v20, 56, v9
	v_sub_u32_e32 v9, 0, v5
	v_ashrrev_i32_e32 v49, 31, v48
	v_lshlrev_b32_e32 v3, 7, v219
	s_add_i32 s88, 0, 0x10000
	v_lshlrev_b32_e32 v6, 4, v6
	v_cmp_gt_u32_e64 s[40:41], v7, v9
	v_sub_u32_e32 v9, 1, v5
	v_lshlrev_b64 v[50:51], 11, v[48:49]
	v_add3_u32 v49, s88, v3, v6
	v_lshl_or_b32 v3, s20, 6, v220
	v_or_b32_e32 v52, 8, v42
	v_cmp_lt_u32_e64 s[42:43], v9, v7
	v_sub_u32_e32 v9, 2, v5
	s_lshl_b32 s30, s82, 10
	v_lshlrev_b32_e32 v57, 3, v3
	v_lshlrev_b32_e32 v59, 5, v3
	v_lshrrev_b32_e32 v3, 1, v48
	v_lshrrev_b32_e32 v10, 1, v52
	v_cmp_lt_u32_e64 s[44:45], v9, v7
	v_sub_u32_e32 v9, 3, v5
	s_add_i32 s84, 0, 0x20000
	v_lshl_add_u32 v194, v245, 2, s84
	v_add_u32_e32 v195, -4, v194
	v_add_u32_e32 v196, -8, v194
	v_add_u32_e32 v197, -12, v194
	v_add_u32_e32 v198, -16, v194
	v_add_u32_e32 v199, -20, v194
	v_add_u32_e32 v200, -24, v194
	v_add_u32_e32 v201, -28, v194
	s_and_b32 s85, s82, -4
	s_add_i32 s86, s30, 0
	s_and_b32 s87, s82, 4
	v_xor_b32_e32 v3, v3, v218
	v_xor_b32_e32 v6, v39, v220
	v_xor_b32_e32 v10, v10, v220
	v_cmp_lt_u32_e64 s[46:47], v9, v7
	v_sub_u32_e32 v9, 4, v5
	s_cmp_eq_u32 s85, 4
	v_bitop3_b32 v4, v4, v43, 4 bitop3:0x6c
	v_lshlrev_b32_e32 v6, 3, v6
	v_lshlrev_b32_e32 v10, 3, v10
	v_cmp_lt_u32_e64 s[48:49], v9, v7
	v_sub_u32_e32 v9, 5, v5
	v_lshlrev_b32_e32 v3, 4, v3
	v_readlane_b32 s13, v163, 40
	v_lshlrev_b32_e32 v2, 3, v2
	s_cselect_b64 s[36:37], -1, 0
	s_cmp_lt_u32 s82, 4
	v_lshlrev_b32_e32 v4, 3, v4
	v_and_b32_e32 v6, 56, v6
	v_lshlrev_b32_e32 v8, 3, v8
	v_and_b32_e32 v10, 56, v10
	v_lshlrev_b32_e32 v12, 3, v12
	v_cmp_lt_u32_e64 s[50:51], v9, v7
	v_sub_u32_e32 v9, 6, v5
	v_sub_u32_e32 v5, 7, v5
	v_and_b32_e32 v22, 0x70, v3
	v_mov_b32_e32 v23, v1
	v_lshl_add_u32 v53, v218, 2, s84
	s_cselect_b64 s[12:13], -1, 0
	s_cbranch_scc0 .Latt_noprio
	s_setprio 1
.Latt_noprio:
	s_add_i32 s88, s88, s30
	v_or_b32_e32 v54, 16, v42
	v_or_b32_e32 v58, 32, v42
	v_or_b32_e32 v62, 48, v42
	v_cmp_lt_u32_e64 s[52:53], v9, v7
	v_cmp_lt_u32_e64 s[54:55], v5, v7
	s_or_b32 s89, s85, 1
	s_or_b32 s90, s85, 2
	s_or_b32 s91, s82, 3
	v_lshl_add_u32 v61, v11, 7, 0
	v_lshl_add_u64 v[66:67], s[18:19], 0, v[0:1]
	v_lshl_add_u64 v[68:69], s[34:35], 0, v[22:23]
	v_lshlrev_b32_e32 v70, 1, v4
	v_lshlrev_b32_e32 v72, 1, v6
	v_lshlrev_b32_e32 v74, 1, v8
	v_lshlrev_b32_e32 v76, 1, v10
	v_lshlrev_b32_e32 v78, 1, v12
	v_lshlrev_b32_e32 v80, 1, v14
	v_lshlrev_b32_e32 v82, 1, v16
	v_lshlrev_b32_e32 v84, 1, v18
	v_lshlrev_b32_e32 v86, 1, v20
	v_lshlrev_b32_e32 v88, 1, v0
	v_lshlrev_b32_e32 v0, 1, v2
	v_lshlrev_b32_e32 v90, 1, v38
	s_mov_b32 s92, s2
	s_branch .LBB0_448

; #define GSYNC() xcd_barrier(xbar)
; __global__ void __launch_bounds__(NWAVES * 64, 2) mega_fwd(Params p) {
;     ...
;             attn_phase(WSP(bf16_t, OFF_Q), WSP(bf16_t, OFF_K), WSP(bf16_t, OFF_VTA), rpb, WSP(bf16_t, OFF_Y), lds, bx, G, tid, wave, lane);
;             if (!((bx >> 3) & 1)) {
;                 for (int u = gw; u < 2048; u += NGW) gmlp_unit(WSP(bf16_t, OFF_VTG), WSP(float, OFF_LNSP) + (size_t)l * T * 16, p.in[3] + l * 1024, p.in[4] + l * 1024, wsb, p.in[6] + l * 1024, WSP(bf16_t, OFF_U), WSP(bf16_t, OFF_Y), u, lane);
;             }
;         }
;         GSYNC();
.LBB0_469:
	s_setprio 0
	v_readlane_b32 s88, v163, 21
	v_readlane_b32 s12, v163, 23
	v_readlane_b32 s90, v163, 27
	v_readlane_b32 s84, v163, 29
	v_readlane_b32 s60, v163, 31
	v_readlane_b32 s46, v163, 47
	v_readlane_b32 s74, v163, 20
	v_readlane_b32 s89, v163, 22
	s_mov_b32 s80, s12
	v_readlane_b32 s75, v163, 25
	v_readlane_b32 s93, v163, 26
	v_readlane_b32 s91, v163, 28
	v_readlane_b32 s85, v163, 30
	v_readlane_b32 s61, v163, 32
	v_readlane_b32 s92, v163, 33
	v_readlane_b32 s52, v163, 34
	v_readlane_b32 s53, v163, 35
	s_movk_i32 s54, 0x2000
	s_movk_i32 s55, 0x4000
	s_movk_i32 s56, 0x6000
	s_mov_b32 s57, 0x18000
	s_mov_b32 s58, 0x8000
	s_movk_i32 s94, 0x1000
	s_movk_i32 s95, 0x3000
	s_mov_b32 s86, 0x20000
	s_mov_b32 s87, 0x28000
	s_mov_b32 s50, 0x30000
	v_readlane_b32 s47, v163, 48
	v_readlane_b32 s13, v163, 24
